# additionally nt on the spatial phase's read-once dwordx4 loads (V^T and U tiles, LN stats partials)
# baseline (speedup 1.0000x reference)
.LBB0_910:
	s_or_b64 exec, exec, s[8:9]
	s_load_dwordx4 s[8:11], s[0:1], 0x38
	s_mul_i32 s13, s28, 0x3000
	s_mul_hi_u32 s12, s28, 0x3000
	v_and_b32_e32 v156, 15, v98
	v_ashrrev_i32_e32 v124, 4, v98
	s_waitcnt lgkmcnt(0)
	s_add_u32 s8, s8, s13
	s_addc_u32 s9, s9, s12
	s_add_u32 s10, s10, s13
	s_addc_u32 s11, s11, s12
	v_readlane_b32 s12, v254, 1
	v_lshlrev_b32_e32 v0, 4, v156
	v_readlane_b32 s13, v254, 2
	v_add_u32_e32 v18, 32, v124
	v_add_u32_e32 v20, 64, v124
	v_lshl_add_u64 v[126:127], s[12:13], 0, v[0:1]
	v_add_u32_e32 v22, 0x60, v124
	v_readlane_b32 s12, v254, 26
	v_ashrrev_i32_e32 v125, 31, v124
	v_ashrrev_i32_e32 v19, 31, v18
	v_ashrrev_i32_e32 v21, 31, v20
	v_ashrrev_i32_e32 v23, 31, v22
	v_readlane_b32 s13, v254, 27
	v_lshlrev_b64 v[2:3], 8, v[124:125]
	v_lshlrev_b64 v[4:5], 8, v[18:19]
	v_lshlrev_b64 v[10:11], 8, v[20:21]
	v_lshlrev_b64 v[12:13], 8, v[22:23]
	v_lshl_add_u64 v[24:25], s[12:13], 0, v[0:1]
	v_lshlrev_b64 v[26:27], 16, v[124:125]
	v_lshlrev_b64 v[18:19], 16, v[18:19]
	v_lshl_add_u64 v[2:3], v[126:127], 0, v[2:3]
	v_lshl_add_u64 v[6:7], v[126:127], 0, v[4:5]
	v_lshl_add_u64 v[10:11], v[126:127], 0, v[10:11]
	v_lshl_add_u64 v[14:15], v[126:127], 0, v[12:13]
	v_lshl_add_u64 v[26:27], v[24:25], 0, v[26:27]
	v_lshl_add_u64 v[18:19], v[24:25], 0, v[18:19]
	global_load_dwordx4 v[2:5], v[2:3], off nt
	s_nop 0
	global_load_dwordx4 v[6:9], v[6:7], off nt
	s_nop 0
	global_load_dwordx4 v[10:13], v[10:11], off nt
	s_nop 0
	global_load_dwordx4 v[14:17], v[14:15], off nt
	s_nop 0
	global_load_dwordx4 v[46:49], v[26:27], off nt
	global_load_dwordx4 v[38:41], v[18:19], off nt
	v_lshlrev_b64 v[18:19], 16, v[20:21]
	v_lshlrev_b64 v[28:29], 2, v[124:125]
	v_lshl_add_u64 v[18:19], v[24:25], 0, v[18:19]
	v_lshlrev_b64 v[20:21], 16, v[22:23]
	v_lshl_add_u64 v[130:131], s[8:9], 0, v[28:29]
	v_lshl_add_u64 v[132:133], s[10:11], 0, v[28:29]
	v_lshl_add_u64 v[20:21], v[24:25], 0, v[20:21]
	global_load_dwordx4 v[34:37], v[18:19], off nt
	global_load_dwordx4 v[26:29], v[20:21], off nt
	global_load_dword v96, v[130:131], off
	global_load_dword v94, v[130:131], off offset:128
	global_load_dword v92, v[130:131], off offset:256
	global_load_dword v90, v[130:131], off offset:384
	global_load_dword v97, v[132:133], off
	global_load_dword v95, v[132:133], off offset:128
	global_load_dword v93, v[132:133], off offset:256
	global_load_dword v91, v[132:133], off offset:384
	v_ashrrev_i32_e32 v53, 2, v98
	v_and_b32_e32 v50, -16, v53
	v_lshrrev_b32_e32 v20, 2, v98
	v_and_b32_e32 v18, 16, v98
	v_readlane_b32 s12, v254, 36
	v_ashrrev_i32_e32 v51, 31, v50
	v_and_b32_e32 v52, 8, v20
	v_or3_b32 v22, v18, s12, v156
	v_lshl_add_u64 v[18:19], v[50:51], 1, s[60:61]
	v_lshlrev_b32_e32 v20, 1, v52
	v_mov_b32_e32 v21, v1
	v_readlane_b32 s13, v254, 37
	v_lshl_add_u64 v[134:135], v[18:19], 0, v[20:21]
	v_or_b32_e32 v20, 32, v22
	v_mad_i64_i32 v[18:19], s[12:13], v22, s85, v[134:135]
	v_mad_i64_i32 v[20:21], s[12:13], v20, s85, v[134:135]
	global_load_dwordx4 v[42:45], v[18:19], off nt
	global_load_dwordx4 v[30:33], v[20:21], off nt
	v_or_b32_e32 v18, 64, v22
	v_or_b32_e32 v20, 0x60, v22
	v_mad_i64_i32 v[18:19], s[12:13], v18, s85, v[134:135]
	v_mad_i64_i32 v[20:21], s[12:13], v20, s85, v[134:135]
	global_load_dwordx4 v[22:25], v[18:19], off nt
	s_nop 0
	global_load_dwordx4 v[18:21], v[20:21], off nt
	v_lshlrev_b32_e32 v125, 3, v98
	v_readlane_b32 s12, v255, 13
	v_bfi_b32 v53, -16, v53, v98
	s_movk_i32 s15, 0x110
	v_add_u32_e32 v157, s12, v125
	s_add_i32 s12, 0, 0x1a000
	v_add_u32_e32 v158, s12, v125
	v_readlane_b32 s12, v255, 14
	v_mul_lo_u32 v53, v53, s15
	v_and_b32_e32 v57, 48, v98
	v_lshl_add_u32 v159, v98, 2, s12
	v_lshl_add_u32 v161, v156, 2, s12
	v_readlane_b32 s12, v254, 24
	v_readlane_b32 s14, v255, 12
	v_lshlrev_b32_e32 v55, 6, v156
	v_add3_u32 v160, 0, v53, v57
	v_readlane_b32 s13, v254, 25
	v_mul_u32_u24_e32 v53, 0x110, v156
	v_add_u32_e32 v54, s14, v0
	v_add_u32_e32 v56, 0, v0
	v_lshl_add_u64 v[136:137], s[12:13], 0, v[0:1]
	v_mul_lo_u32 v0, v124, s15
	v_add3_u32 v165, s14, v57, v53
	v_add_u32_e32 v53, 0, v55
	v_mov_b32_e32 v101, v1
	v_bfe_u32 v162, v98, 4, 1
	v_add_u32_e32 v163, 0x80, v124
	v_and_b32_e32 v164, 31, v98
	v_add_u32_e32 v166, v54, v0
	v_add_u32_e32 v167, 0x1a000, v53
	v_add_u32_e32 v168, v56, v0
	v_lshlrev_b64 v[138:139], 1, v[50:51]
	v_lshlrev_b32_e32 v0, 1, v52
	v_readlane_b32 s15, v254, 0
	s_branch .LBB0_913
.LBB0_911:
	s_or_b64 exec, exec, s[18:19]
	v_add_u32_e32 v2, s17, v124
	v_ashrrev_i32_e32 v3, 31, v2
	v_lshl_add_u32 v18, s15, 8, v2
	v_lshlrev_b64 v[2:3], 8, v[2:3]
	s_mul_i32 s42, s15, 0x300
	v_lshl_add_u64 v[10:11], v[126:127], 0, v[2:3]
	s_movk_i32 s15, 0x2000
	v_add_co_u32_e32 v6, vcc, s15, v10
	s_movk_i32 s15, 0x4000
	s_nop 0
	v_addc_co_u32_e32 v7, vcc, 0, v11, vcc
	s_and_b32 s16, s16, 0xffffff80
	v_add_co_u32_e32 v12, vcc, s15, v10
	s_ashr_i32 s17, s16, 31
	s_nop 0
	v_addc_co_u32_e32 v13, vcc, 0, v11, vcc
	s_movk_i32 s15, 0x6000
	v_ashrrev_i32_e32 v19, 31, v18
	v_lshl_add_u64 v[20:21], s[16:17], 1, v[136:137]
	v_add_co_u32_e32 v14, vcc, s15, v10
	v_lshlrev_b64 v[22:23], 16, v[18:19]
	s_nop 0
	v_addc_co_u32_e32 v15, vcc, 0, v11, vcc
	v_lshl_add_u64 v[20:21], v[20:21], 0, v[22:23]
	s_mov_b32 s15, 0x200000
	v_add_co_u32_e32 v24, vcc, s15, v20
	s_mov_b32 s15, 0x400000
	s_nop 0
	v_addc_co_u32_e32 v25, vcc, 0, v21, vcc
	v_lshlrev_b64 v[18:19], 2, v[18:19]
	v_add_co_u32_e32 v26, vcc, s15, v20
	v_lshl_add_u64 v[22:23], s[8:9], 0, v[18:19]
	s_nop 0
	v_addc_co_u32_e32 v27, vcc, 0, v21, vcc
	v_or_b32_e32 v52, s16, v164
	v_lshl_add_u64 v[50:51], v[134:135], 0, s[42:43]
	global_load_dwordx4 v[2:5], v[10:11], off nt
	s_nop 0
	global_load_dwordx4 v[6:9], v[6:7], off nt
	s_nop 0
	global_load_dwordx4 v[10:13], v[12:13], off nt
	s_nop 0
	global_load_dwordx4 v[14:17], v[14:15], off nt
	v_lshl_add_u64 v[18:19], s[10:11], 0, v[18:19]
	global_load_dwordx4 v[46:49], v[20:21], off nt
	global_load_dwordx4 v[38:41], v[24:25], off nt
	global_load_dwordx4 v[34:37], v[26:27], off nt
	v_add_co_u32_e32 v20, vcc, s27, v20
	global_load_dword v96, v[22:23], off
	global_load_dword v94, v[22:23], off offset:128
	global_load_dword v92, v[22:23], off offset:256
	global_load_dword v90, v[22:23], off offset:384
	global_load_dword v97, v[18:19], off
	global_load_dword v95, v[18:19], off offset:128
	global_load_dword v93, v[18:19], off offset:256
	global_load_dword v91, v[18:19], off offset:384
	v_addc_co_u32_e32 v21, vcc, 0, v21, vcc
	v_mad_i64_i32 v[18:19], s[16:17], v52, s85, v[50:51]
	global_load_dwordx4 v[26:29], v[20:21], off nt
	global_load_dwordx4 v[42:45], v[18:19], off nt
	v_or_b32_e32 v18, 32, v52
	v_mad_i64_i32 v[18:19], s[16:17], v18, s85, v[50:51]
	v_or_b32_e32 v20, 64, v52
	v_mad_i64_i32 v[20:21], s[16:17], v20, s85, v[50:51]
	global_load_dwordx4 v[30:33], v[18:19], off nt
	global_load_dwordx4 v[22:25], v[20:21], off nt
	v_or_b32_e32 v18, 0x60, v52
	v_mad_i64_i32 v[18:19], s[16:17], v18, s85, v[50:51]
	global_load_dwordx4 v[18:21], v[18:19], off nt

.LBB0_919:
	s_or_b64 exec, exec, s[12:13]
	s_waitcnt lgkmcnt(0)
	s_barrier
	s_waitcnt vmcnt(19)
	ds_write_b128 v166, v[2:5]
	s_waitcnt vmcnt(18)
	ds_write_b128 v166, v[6:9] offset:8704
	s_waitcnt vmcnt(17)
	ds_write_b128 v166, v[10:13] offset:17408
	s_waitcnt vmcnt(16)
	ds_write_b128 v166, v[14:17] offset:26112
	ds_read_b128 v[50:53], v167
	ds_read_b128 v[54:57], v167 offset:16
	ds_read_b128 v[58:61], v167 offset:32
	ds_read_b128 v[62:65], v167 offset:48
	s_waitcnt vmcnt(15)
	v_lshlrev_b32_e32 v66, 16, v46
	s_waitcnt lgkmcnt(3)
	v_sub_f32_e32 v50, v66, v50
	v_and_b32_e32 v46, 0xffff0000, v46
	v_mul_f32_e32 v50, v51, v50
	v_sub_f32_e32 v46, v46, v52
	v_lshlrev_b32_e32 v51, 16, v47
	v_and_b32_e32 v47, 0xffff0000, v47
	v_lshlrev_b32_e32 v52, 16, v48
	v_and_b32_e32 v48, 0xffff0000, v48
	v_mul_f32_e32 v46, v53, v46
	s_waitcnt lgkmcnt(2)
	v_sub_f32_e32 v47, v47, v56
	s_waitcnt lgkmcnt(1)
	v_sub_f32_e32 v48, v48, v60
	v_lshlrev_b32_e32 v53, 16, v49
	v_and_b32_e32 v49, 0xffff0000, v49
	v_sub_f32_e32 v51, v51, v54
	v_mul_f32_e32 v47, v57, v47
	v_sub_f32_e32 v52, v52, v58
	v_mul_f32_e32 v48, v61, v48
	s_waitcnt lgkmcnt(0)
	v_sub_f32_e32 v53, v53, v62
	v_sub_f32_e32 v49, v49, v64
	s_waitcnt vmcnt(7)
	v_fma_f32 v46, v96, v46, v97
	v_mul_f32_e32 v51, v55, v51
	v_fma_f32 v47, v96, v47, v97
	v_mul_f32_e32 v52, v59, v52
	v_fma_f32 v48, v96, v48, v97
	v_mul_f32_e32 v53, v63, v53
	v_mul_f32_e32 v49, v65, v49
	v_fma_f32 v50, v96, v50, v97
	v_fma_f32 v51, v96, v51, v97
	v_fma_f32 v52, v96, v52, v97
	v_fma_f32 v53, v96, v53, v97
	v_fmac_f32_e32 v97, v96, v49
	v_cvt_pk_bf16_f32 v46, v50, v46
	v_cvt_pk_bf16_f32 v47, v51, v47
	v_cvt_pk_bf16_f32 v48, v52, v48
	v_cvt_pk_bf16_f32 v49, v53, v97
	ds_write_b128 v168, v[46:49]
	ds_read_b128 v[46:49], v167
	ds_read_b128 v[50:53], v167 offset:16
	ds_read_b128 v[54:57], v167 offset:32
	ds_read_b128 v[58:61], v167 offset:48
	v_lshlrev_b32_e32 v62, 16, v38
	s_waitcnt lgkmcnt(3)
	v_sub_f32_e32 v46, v62, v46
	v_and_b32_e32 v38, 0xffff0000, v38
	v_mul_f32_e32 v46, v47, v46
	v_sub_f32_e32 v38, v38, v48
	v_lshlrev_b32_e32 v47, 16, v39
	v_and_b32_e32 v39, 0xffff0000, v39
	v_lshlrev_b32_e32 v48, 16, v40
	v_and_b32_e32 v40, 0xffff0000, v40
	v_mul_f32_e32 v38, v49, v38
	s_waitcnt lgkmcnt(2)
	v_sub_f32_e32 v39, v39, v52
	s_waitcnt lgkmcnt(1)
	v_sub_f32_e32 v40, v40, v56
	v_lshlrev_b32_e32 v49, 16, v41
	v_and_b32_e32 v41, 0xffff0000, v41
	v_sub_f32_e32 v47, v47, v50
	v_mul_f32_e32 v39, v53, v39
	v_sub_f32_e32 v48, v48, v54
	v_mul_f32_e32 v40, v57, v40
	s_waitcnt lgkmcnt(0)
	v_sub_f32_e32 v49, v49, v58
	v_sub_f32_e32 v41, v41, v60
	s_waitcnt vmcnt(6)
	v_fma_f32 v38, v94, v38, v95
	v_mul_f32_e32 v47, v51, v47
	v_fma_f32 v39, v94, v39, v95
	v_mul_f32_e32 v48, v55, v48
	v_fma_f32 v40, v94, v40, v95
	v_mul_f32_e32 v49, v59, v49
	v_mul_f32_e32 v41, v61, v41
	v_fma_f32 v46, v94, v46, v95
	v_fma_f32 v47, v94, v47, v95
	v_fma_f32 v48, v94, v48, v95
	v_fma_f32 v49, v94, v49, v95
	v_fmac_f32_e32 v95, v94, v41
	v_cvt_pk_bf16_f32 v38, v46, v38
	v_cvt_pk_bf16_f32 v39, v47, v39
	v_cvt_pk_bf16_f32 v40, v48, v40
	v_cvt_pk_bf16_f32 v41, v49, v95
	ds_write_b128 v168, v[38:41] offset:8704
	ds_read_b128 v[38:41], v167
	ds_read_b128 v[46:49], v167 offset:16
	ds_read_b128 v[50:53], v167 offset:32
	ds_read_b128 v[54:57], v167 offset:48
	v_lshlrev_b32_e32 v58, 16, v34
	s_waitcnt lgkmcnt(3)
	v_sub_f32_e32 v38, v58, v38
	v_and_b32_e32 v34, 0xffff0000, v34
	v_mul_f32_e32 v38, v39, v38
	v_sub_f32_e32 v34, v34, v40
	v_lshlrev_b32_e32 v39, 16, v35
	v_and_b32_e32 v35, 0xffff0000, v35
	v_lshlrev_b32_e32 v40, 16, v36
	v_and_b32_e32 v36, 0xffff0000, v36
	v_mul_f32_e32 v34, v41, v34
	s_waitcnt lgkmcnt(2)
	v_sub_f32_e32 v35, v35, v48
	s_waitcnt lgkmcnt(1)
	v_sub_f32_e32 v36, v36, v52
	v_lshlrev_b32_e32 v41, 16, v37
	v_and_b32_e32 v37, 0xffff0000, v37
	v_sub_f32_e32 v39, v39, v46
	v_mul_f32_e32 v35, v49, v35
	v_sub_f32_e32 v40, v40, v50
	v_mul_f32_e32 v36, v53, v36
	s_waitcnt lgkmcnt(0)
	v_sub_f32_e32 v41, v41, v54
	v_sub_f32_e32 v37, v37, v56
	s_waitcnt vmcnt(5)
	v_fma_f32 v34, v92, v34, v93
	v_mul_f32_e32 v39, v47, v39
	v_fma_f32 v35, v92, v35, v93
	v_mul_f32_e32 v40, v51, v40
	v_fma_f32 v36, v92, v36, v93
	v_mul_f32_e32 v41, v55, v41
	v_mul_f32_e32 v37, v57, v37
	v_fma_f32 v38, v92, v38, v93
	v_fma_f32 v39, v92, v39, v93
	v_fma_f32 v40, v92, v40, v93
	v_fma_f32 v41, v92, v41, v93
	v_fmac_f32_e32 v93, v92, v37
	v_cvt_pk_bf16_f32 v34, v38, v34
	v_cvt_pk_bf16_f32 v35, v39, v35
	v_cvt_pk_bf16_f32 v36, v40, v36
	v_cvt_pk_bf16_f32 v37, v41, v93
	ds_write_b128 v168, v[34:37] offset:17408
	ds_read_b128 v[34:37], v167
	ds_read_b128 v[38:41], v167 offset:16
	ds_read_b128 v[46:49], v167 offset:32
	ds_read_b128 v[50:53], v167 offset:48
	s_lshl_b32 s12, s15, 4
	v_lshlrev_b32_e32 v54, 16, v26
	s_and_b32 s16, s12, 0xffffff80
	s_waitcnt lgkmcnt(3)
	v_sub_f32_e32 v34, v54, v34
	v_and_b32_e32 v26, 0xffff0000, v26
	s_cmp_eq_u32 s17, 7
	v_mul_f32_e32 v34, v35, v34
	v_sub_f32_e32 v26, v26, v36
	v_lshlrev_b32_e32 v35, 16, v27
	v_and_b32_e32 v27, 0xffff0000, v27
	v_lshlrev_b32_e32 v36, 16, v28
	v_and_b32_e32 v28, 0xffff0000, v28
	s_cselect_b32 s14, s26, 1
	v_mul_f32_e32 v26, v37, v26
	s_waitcnt lgkmcnt(2)
	v_sub_f32_e32 v27, v27, v40
	s_waitcnt lgkmcnt(1)
	v_sub_f32_e32 v28, v28, v48
	v_lshlrev_b32_e32 v37, 16, v29
	v_and_b32_e32 v29, 0xffff0000, v29
	s_add_i32 s14, s14, s15
	v_sub_f32_e32 v35, v35, v38
	v_mul_f32_e32 v27, v41, v27
	v_sub_f32_e32 v36, v36, v46
	v_mul_f32_e32 v28, v49, v28
	s_waitcnt lgkmcnt(0)
	v_sub_f32_e32 v37, v37, v50
	v_sub_f32_e32 v29, v29, v52
	s_cmpk_gt_i32 s14, 0x7ff
	s_waitcnt vmcnt(4)
	v_fma_f32 v26, v90, v26, v91
	v_mul_f32_e32 v35, v39, v35
	v_fma_f32 v27, v90, v27, v91
	v_mul_f32_e32 v36, v47, v36
	v_fma_f32 v28, v90, v28, v91
	v_mul_f32_e32 v37, v51, v37
	v_mul_f32_e32 v29, v53, v29
	s_mul_i32 s18, s17, 0x180
	s_cselect_b64 s[12:13], -1, 0
	v_fma_f32 v34, v90, v34, v91
	v_fma_f32 v35, v90, v35, v91
	v_fma_f32 v36, v90, v36, v91
	v_fma_f32 v37, v90, v37, v91
	v_fmac_f32_e32 v91, v90, v29
	v_cvt_pk_bf16_f32 v26, v34, v26
	v_cvt_pk_bf16_f32 v27, v35, v27
	v_cvt_pk_bf16_f32 v28, v36, v28
	v_cvt_pk_bf16_f32 v29, v37, v91
	s_and_b32 s15, s15, 0xffffff8
	s_lshl_b32 s42, s18, 1
	s_ashr_i32 s17, s16, 31
	ds_write_b128 v168, v[26:29] offset:26112
	v_lshl_add_u64 v[28:29], s[16:17], 1, v[136:137]
	v_or_b32_e32 v66, s16, v164
	s_add_u32 s16, s60, s42
	s_addc_u32 s17, s61, 0
	v_mov_b64_e32 v[50:51], s[16:17]
	v_mad_i64_i32 v[52:53], s[16:17], v66, s85, v[50:51]
	v_lshl_add_u64 v[52:53], v[52:53], 0, v[138:139]
	v_add_u32_e32 v26, s18, v163
	v_lshl_add_u64 v[146:147], v[52:53], 0, v[0:1]
	v_or_b32_e32 v52, 32, v66
	v_ashrrev_i32_e32 v27, 31, v26
	v_mad_i64_i32 v[52:53], s[16:17], v52, s85, v[50:51]
	v_lshlrev_b64 v[26:27], 16, v[26:27]
	v_lshl_add_u64 v[52:53], v[52:53], 0, v[138:139]
	v_or_b32_e32 v177, s15, v162
	v_lshl_add_u64 v[140:141], v[28:29], 0, v[26:27]
	s_mov_b32 s15, 0x200000
	v_lshl_add_u64 v[148:149], v[52:53], 0, v[0:1]
	v_or_b32_e32 v52, 64, v66
	v_lshl_add_u64 v[154:155], v[134:135], 0, s[42:43]
	s_lshl_b32 s42, s18, 2
	v_add_co_u32_e32 v26, vcc, s15, v140
	v_mad_i64_i32 v[52:53], s[16:17], v52, s85, v[50:51]
	v_lshl_add_u64 v[142:143], v[130:131], 0, s[42:43]
	v_lshl_add_u64 v[144:145], v[132:133], 0, s[42:43]
	v_addc_co_u32_e32 v27, vcc, 0, v141, vcc
	s_mov_b32 s15, 0x400000
	v_lshl_add_u64 v[52:53], v[52:53], 0, v[138:139]
	s_waitcnt lgkmcnt(0)
	s_barrier
	global_load_dwordx4 v[46:49], v[140:141], off nt
	global_load_dword v176, v[142:143], off offset:512
	global_load_dword v175, v[144:145], off offset:512
	global_load_dwordx4 v[38:41], v[26:27], off nt
	global_load_dword v174, v[142:143], off offset:640
	global_load_dword v173, v[144:145], off offset:640
	v_add_co_u32_e32 v26, vcc, s15, v140
	v_lshl_add_u64 v[150:151], v[52:53], 0, v[0:1]
	v_or_b32_e32 v52, 0x60, v66
	v_addc_co_u32_e32 v27, vcc, 0, v141, vcc
	v_mad_i64_i32 v[50:51], s[16:17], v52, s85, v[50:51]
	global_load_dwordx4 v[34:37], v[26:27], off nt
	global_load_dword v172, v[142:143], off offset:768
	global_load_dword v171, v[144:145], off offset:768
	v_add_co_u32_e32 v26, vcc, s27, v140
	v_lshl_add_u64 v[50:51], v[50:51], 0, v[138:139]
	s_nop 0
	v_addc_co_u32_e32 v27, vcc, 0, v141, vcc
	v_lshl_add_u64 v[152:153], v[50:51], 0, v[0:1]
	global_load_dwordx4 v[26:29], v[26:27], off nt
	s_nop 0
	global_load_dword v170, v[142:143], off offset:896
	global_load_dword v169, v[144:145], off offset:896
	global_load_dwordx4 v[62:65], v[146:147], off offset:256 nt
	global_load_dwordx4 v[58:61], v[148:149], off offset:256 nt
	global_load_dwordx4 v[54:57], v[150:151], off offset:256 nt
	global_load_dwordx4 v[50:53], v[152:153], off offset:256 nt
	ds_read_b128 v[66:69], v160
	ds_read_b128 v[70:73], v165
	ds_read_b128 v[74:77], v165 offset:4352
	ds_read_b128 v[78:81], v165 offset:8704
	ds_read_b128 v[82:85], v165 offset:13056
	ds_read_b128 v[86:89], v165 offset:17408
	ds_read_b128 v[90:93], v165 offset:21760
	ds_read_b128 v[94:97], v165 offset:26112
	ds_read_b128 v[178:181], v165 offset:30464
	s_waitcnt lgkmcnt(7)
	v_mfma_f32_16x16x32_bf16 v[70:73], v[66:69], v[70:73], 0
	s_waitcnt vmcnt(19)
	v_permlane16_swap_b32_e32 v42, v44
	v_permlane16_swap_b32_e32 v43, v45
	s_waitcnt lgkmcnt(6)
	v_mfma_f32_16x16x32_bf16 v[74:77], v[66:69], v[74:77], 0
	s_waitcnt vmcnt(18)
	v_permlane16_swap_b32_e32 v30, v32
	v_permlane16_swap_b32_e32 v31, v33
	s_waitcnt lgkmcnt(5)
	v_mfma_f32_16x16x32_bf16 v[78:81], v[66:69], v[78:81], 0
	s_waitcnt vmcnt(17)
	v_permlane16_swap_b32_e32 v22, v24
	v_permlane16_swap_b32_e32 v23, v25
	s_waitcnt lgkmcnt(4)
	v_mfma_f32_16x16x32_bf16 v[82:85], v[66:69], v[82:85], 0
	s_waitcnt vmcnt(16)
	v_permlane16_swap_b32_e32 v18, v20
	v_permlane16_swap_b32_e32 v19, v21
	s_waitcnt lgkmcnt(3)
	v_mfma_f32_16x16x32_bf16 v[86:89], v[66:69], v[86:89], 0
	s_mov_b32 s15, 0x800000
	s_waitcnt vmcnt(3)
	v_permlane16_swap_b32_e32 v62, v64
	s_waitcnt lgkmcnt(2)
	v_mfma_f32_16x16x32_bf16 v[90:93], v[66:69], v[90:93], 0
	v_permlane16_swap_b32_e32 v63, v65
	s_waitcnt vmcnt(2)
	v_permlane16_swap_b32_e32 v58, v60
	s_waitcnt lgkmcnt(1)
	v_mfma_f32_16x16x32_bf16 v[94:97], v[66:69], v[94:97], 0
	v_permlane16_swap_b32_e32 v59, v61
	s_waitcnt vmcnt(1)
	v_permlane16_swap_b32_e32 v54, v56
	s_waitcnt lgkmcnt(0)
	v_mfma_f32_16x16x32_bf16 v[66:69], v[66:69], v[178:181], 0
	ds_read_b128 v[178:181], v160 offset:64
	ds_read_b128 v[188:191], v165 offset:64
	v_permlane16_swap_b32_e32 v55, v57
	s_waitcnt lgkmcnt(0)
	v_mfma_f32_16x16x32_bf16 v[70:73], v[178:181], v[188:191], v[70:73]
	ds_read_b128 v[188:191], v165 offset:4416
	s_waitcnt lgkmcnt(0)
	v_mfma_f32_16x16x32_bf16 v[74:77], v[178:181], v[188:191], v[74:77]
	ds_read_b128 v[188:191], v165 offset:8768
	s_waitcnt lgkmcnt(0)
	v_mfma_f32_16x16x32_bf16 v[78:81], v[178:181], v[188:191], v[78:81]
	ds_read_b128 v[188:191], v165 offset:13120
	s_waitcnt lgkmcnt(0)
	v_mfma_f32_16x16x32_bf16 v[82:85], v[178:181], v[188:191], v[82:85]
	ds_read_b128 v[188:191], v165 offset:17472
	s_waitcnt lgkmcnt(0)
	v_mfma_f32_16x16x32_bf16 v[86:89], v[178:181], v[188:191], v[86:89]
	ds_read_b128 v[188:191], v165 offset:21824
	s_waitcnt lgkmcnt(0)
	v_mfma_f32_16x16x32_bf16 v[90:93], v[178:181], v[188:191], v[90:93]
	ds_read_b128 v[188:191], v165 offset:26176
	s_waitcnt lgkmcnt(0)
	v_mfma_f32_16x16x32_bf16 v[94:97], v[178:181], v[188:191], v[94:97]
	ds_read_b128 v[188:191], v165 offset:30528
	s_waitcnt lgkmcnt(0)
	v_mfma_f32_16x16x32_bf16 v[66:69], v[178:181], v[188:191], v[66:69]
	ds_read_b128 v[178:181], v160 offset:128
	ds_read_b128 v[188:191], v165 offset:128
	s_waitcnt lgkmcnt(0)
	v_mfma_f32_16x16x32_bf16 v[70:73], v[178:181], v[188:191], v[70:73]
	ds_read_b128 v[188:191], v165 offset:4480
	s_waitcnt lgkmcnt(0)
	v_mfma_f32_16x16x32_bf16 v[74:77], v[178:181], v[188:191], v[74:77]
	ds_read_b128 v[188:191], v165 offset:8832
	s_waitcnt lgkmcnt(0)
	v_mfma_f32_16x16x32_bf16 v[78:81], v[178:181], v[188:191], v[78:81]
	ds_read_b128 v[188:191], v165 offset:13184
	s_waitcnt lgkmcnt(0)
	v_mfma_f32_16x16x32_bf16 v[82:85], v[178:181], v[188:191], v[82:85]
	ds_read_b128 v[188:191], v165 offset:17536
	s_waitcnt lgkmcnt(0)
	v_mfma_f32_16x16x32_bf16 v[188:191], v[178:181], v[188:191], v[86:89]
	s_nop 2
	ds_read_b128 v[86:89], v165 offset:21888
	s_waitcnt lgkmcnt(0)
	v_mfma_f32_16x16x32_bf16 v[192:195], v[178:181], v[86:89], v[90:93]
	ds_read_b128 v[86:89], v165 offset:26240
	s_waitcnt lgkmcnt(0)
	v_mfma_f32_16x16x32_bf16 v[196:199], v[178:181], v[86:89], v[94:97]
	ds_read_b128 v[86:89], v165 offset:30592
	s_waitcnt lgkmcnt(0)
	v_mfma_f32_16x16x32_bf16 v[66:69], v[178:181], v[86:89], v[66:69]
	ds_read_b128 v[178:181], v160 offset:192
	ds_read_b128 v[86:89], v165 offset:192
	s_waitcnt lgkmcnt(0)
	v_mfma_f32_16x16x32_bf16 v[86:89], v[178:181], v[86:89], v[70:73]
	s_nop 2
	ds_read_b128 v[70:73], v165 offset:4544
	s_waitcnt lgkmcnt(0)
	v_mfma_f32_16x16x32_bf16 v[94:97], v[178:181], v[70:73], v[74:77]
	ds_read_b128 v[70:73], v165 offset:8896
	s_nop 1
	ds_read_b128 v[74:77], v165 offset:21952
	s_waitcnt lgkmcnt(1)
	v_mfma_f32_16x16x32_bf16 v[78:81], v[178:181], v[70:73], v[78:81]
	ds_read_b128 v[70:73], v165 offset:13248
	s_waitcnt lgkmcnt(0)
	v_mfma_f32_16x16x32_bf16 v[90:93], v[178:181], v[70:73], v[82:85]
	ds_read_b128 v[70:73], v165 offset:17600
	v_mfma_f32_16x16x32_bf16 v[82:85], v[178:181], v[74:77], v[192:195]
	ds_read_b128 v[74:77], v165 offset:26304
	s_waitcnt lgkmcnt(1)
	v_mfma_f32_16x16x32_bf16 v[70:73], v[178:181], v[70:73], v[188:191]
	s_nop 2
	ds_read_b128 v[188:191], v165 offset:30656
	s_waitcnt lgkmcnt(1)
	v_mfma_f32_16x16x32_bf16 v[74:77], v[178:181], v[74:77], v[196:199]
	s_waitcnt lgkmcnt(0)
	v_mfma_f32_16x16x32_bf16 v[66:69], v[178:181], v[188:191], v[66:69]
	ds_read2_b32 v[178:179], v161 offset1:16
	v_lshlrev_b32_e32 v180, 16, v42
	v_and_b32_e32 v42, 0xffff0000, v42
	s_waitcnt lgkmcnt(0)
	v_add_f32_e32 v86, v86, v178
	v_add_f32_e32 v87, v87, v178
	v_mul_f32_e32 v86, v86, v180
	v_mul_f32_e32 v42, v87, v42
	v_cvt_pk_bf16_f32 v42, v86, v42
	v_add_f32_e32 v86, v88, v178
	v_lshlrev_b32_e32 v87, 16, v43
	v_mul_f32_e32 v86, v86, v87
	v_add_f32_e32 v87, v89, v178
	v_and_b32_e32 v43, 0xffff0000, v43
	v_mul_f32_e32 v43, v87, v43
	v_cvt_pk_bf16_f32 v43, v86, v43
	v_add_f32_e32 v86, v94, v179
	v_lshlrev_b32_e32 v87, 16, v44
	v_mul_f32_e32 v86, v86, v87
	v_add_f32_e32 v87, v95, v179
	v_and_b32_e32 v44, 0xffff0000, v44
	v_mul_f32_e32 v44, v87, v44
	v_cvt_pk_bf16_f32 v44, v86, v44
	v_add_f32_e32 v86, v96, v179
	v_lshlrev_b32_e32 v87, 16, v45
	v_mul_f32_e32 v86, v86, v87
	v_add_f32_e32 v87, v97, v179
	v_and_b32_e32 v45, 0xffff0000, v45
	v_mul_f32_e32 v45, v87, v45
	v_cvt_pk_bf16_f32 v45, v86, v45
	v_lshl_or_b32 v94, v177, 4, v156
	v_permlane16_swap_b32_e32 v42, v44
	v_permlane16_swap_b32_e32 v43, v45
	v_mad_i64_i32 v[88:89], s[16:17], v94, s85, v[154:155]
	global_store_dwordx4 v[88:89], v[42:45], off
	ds_read2_b32 v[42:43], v161 offset0:32 offset1:48
	s_nop 0
	v_lshlrev_b32_e32 v45, 16, v30
	v_and_b32_e32 v30, 0xffff0000, v30
	s_waitcnt lgkmcnt(0)
	v_add_f32_e32 v44, v78, v42
	v_mul_f32_e32 v44, v44, v45
	v_add_f32_e32 v45, v79, v42
	v_mul_f32_e32 v30, v45, v30
	v_cvt_pk_bf16_f32 v30, v44, v30
	v_add_f32_e32 v44, v80, v42
	v_lshlrev_b32_e32 v45, 16, v31
	v_add_f32_e32 v42, v81, v42
	v_and_b32_e32 v31, 0xffff0000, v31
	v_mul_f32_e32 v44, v44, v45
	v_mul_f32_e32 v31, v42, v31
	v_cvt_pk_bf16_f32 v31, v44, v31
	v_add_f32_e32 v42, v90, v43
	v_lshlrev_b32_e32 v44, 16, v32
	v_mul_f32_e32 v42, v42, v44
	v_add_f32_e32 v44, v91, v43
	v_and_b32_e32 v32, 0xffff0000, v32
	v_mul_f32_e32 v32, v44, v32
	v_cvt_pk_bf16_f32 v32, v42, v32
	v_add_f32_e32 v42, v92, v43
	v_lshlrev_b32_e32 v44, 16, v33
	v_add_f32_e32 v43, v93, v43
	v_and_b32_e32 v33, 0xffff0000, v33
	v_mul_f32_e32 v42, v42, v44
	v_mul_f32_e32 v33, v43, v33
	v_cvt_pk_bf16_f32 v33, v42, v33
	v_or_b32_e32 v42, 32, v94
	v_permlane16_swap_b32_e32 v30, v32
	v_permlane16_swap_b32_e32 v31, v33
	v_mad_i64_i32 v[86:87], s[16:17], v42, s85, v[154:155]
	global_store_dwordx4 v[86:87], v[30:33], off
	ds_read2_b32 v[30:31], v161 offset0:64 offset1:80
	s_nop 0
	v_lshlrev_b32_e32 v33, 16, v22
	v_and_b32_e32 v22, 0xffff0000, v22
	s_waitcnt lgkmcnt(0)
	v_add_f32_e32 v32, v70, v30
	v_mul_f32_e32 v32, v32, v33
	v_add_f32_e32 v33, v71, v30
	v_mul_f32_e32 v22, v33, v22
	v_cvt_pk_bf16_f32 v22, v32, v22
	v_add_f32_e32 v32, v72, v30
	v_lshlrev_b32_e32 v33, 16, v23
	v_add_f32_e32 v30, v73, v30
	v_and_b32_e32 v23, 0xffff0000, v23
	v_mul_f32_e32 v32, v32, v33
	v_mul_f32_e32 v23, v30, v23
	v_cvt_pk_bf16_f32 v23, v32, v23
	v_add_f32_e32 v30, v82, v31
	v_lshlrev_b32_e32 v32, 16, v24
	v_mul_f32_e32 v30, v30, v32
	v_add_f32_e32 v32, v83, v31
	v_and_b32_e32 v24, 0xffff0000, v24
	v_mul_f32_e32 v24, v32, v24
	v_cvt_pk_bf16_f32 v24, v30, v24
	v_add_f32_e32 v30, v84, v31
	v_lshlrev_b32_e32 v32, 16, v25
	v_add_f32_e32 v31, v85, v31
	v_and_b32_e32 v25, 0xffff0000, v25
	v_mul_f32_e32 v30, v30, v32
	v_mul_f32_e32 v25, v31, v25
	v_cvt_pk_bf16_f32 v25, v30, v25
	v_or_b32_e32 v30, 64, v94
	v_permlane16_swap_b32_e32 v22, v24
	v_permlane16_swap_b32_e32 v23, v25
	v_mad_i64_i32 v[82:83], s[16:17], v30, s85, v[154:155]
	global_store_dwordx4 v[82:83], v[22:25], off
	ds_read2_b32 v[22:23], v161 offset0:96 offset1:112
	s_nop 0
	v_lshlrev_b32_e32 v25, 16, v18
	v_and_b32_e32 v18, 0xffff0000, v18
	s_waitcnt lgkmcnt(0)
	v_add_f32_e32 v24, v74, v22
	v_mul_f32_e32 v24, v24, v25
	v_add_f32_e32 v25, v75, v22
	v_mul_f32_e32 v18, v25, v18
	v_cvt_pk_bf16_f32 v18, v24, v18
	v_add_f32_e32 v24, v76, v22
	v_lshlrev_b32_e32 v25, 16, v19
	v_add_f32_e32 v22, v77, v22
	v_and_b32_e32 v19, 0xffff0000, v19
	v_mul_f32_e32 v24, v24, v25
	v_mul_f32_e32 v19, v22, v19
	v_cvt_pk_bf16_f32 v19, v24, v19
	v_add_f32_e32 v22, v66, v23
	v_lshlrev_b32_e32 v24, 16, v20
	v_mul_f32_e32 v22, v22, v24
	v_add_f32_e32 v24, v67, v23
	v_and_b32_e32 v20, 0xffff0000, v20
	v_mul_f32_e32 v20, v24, v20
	v_cvt_pk_bf16_f32 v20, v22, v20
	v_add_f32_e32 v22, v68, v23
	v_lshlrev_b32_e32 v24, 16, v21
	v_add_f32_e32 v23, v69, v23
	v_and_b32_e32 v21, 0xffff0000, v21
	v_mul_f32_e32 v22, v22, v24
	v_mul_f32_e32 v21, v23, v21
	v_cvt_pk_bf16_f32 v21, v22, v21
	v_or_b32_e32 v22, 0x60, v94
	v_permlane16_swap_b32_e32 v18, v20
	v_permlane16_swap_b32_e32 v19, v21
	v_mad_i64_i32 v[84:85], s[16:17], v22, s85, v[154:155]
	global_store_dwordx4 v[84:85], v[18:21], off
	ds_read_b128 v[18:21], v167
	ds_read_b128 v[22:25], v167 offset:16
	ds_read_b128 v[30:33], v167 offset:32
	ds_read_b128 v[42:45], v167 offset:48
	v_lshlrev_b32_e32 v66, 16, v46
	s_waitcnt lgkmcnt(3)
	v_sub_f32_e32 v18, v66, v18
	v_mul_f32_e32 v18, v19, v18
	v_and_b32_e32 v19, 0xffff0000, v46
	v_sub_f32_e32 v19, v19, v20
	v_mul_f32_e32 v19, v21, v19
	v_lshlrev_b32_e32 v20, 16, v47
	v_and_b32_e32 v21, 0xffff0000, v47
	s_waitcnt lgkmcnt(2)
	v_sub_f32_e32 v20, v20, v22
	v_sub_f32_e32 v21, v21, v24
	v_mul_f32_e32 v20, v23, v20
	v_mul_f32_e32 v21, v25, v21
	v_lshlrev_b32_e32 v22, 16, v48
	v_and_b32_e32 v23, 0xffff0000, v48
	v_lshlrev_b32_e32 v24, 16, v49
	v_and_b32_e32 v25, 0xffff0000, v49
	s_waitcnt lgkmcnt(1)
	v_sub_f32_e32 v22, v22, v30
	v_sub_f32_e32 v23, v23, v32
	s_waitcnt lgkmcnt(0)
	v_sub_f32_e32 v24, v24, v42
	v_sub_f32_e32 v25, v25, v44
	v_fma_f32 v18, v176, v18, v175
	v_fma_f32 v19, v176, v19, v175
	v_fma_f32 v20, v176, v20, v175
	v_fma_f32 v21, v176, v21, v175
	v_mul_f32_e32 v22, v31, v22
	v_mul_f32_e32 v23, v33, v23
	v_mul_f32_e32 v24, v43, v24
	v_mul_f32_e32 v25, v45, v25
	v_fma_f32 v22, v176, v22, v175
	v_fma_f32 v23, v176, v23, v175
	v_fma_f32 v24, v176, v24, v175
	v_fmac_f32_e32 v175, v176, v25
	v_cvt_pk_bf16_f32 v18, v18, v19
	v_cvt_pk_bf16_f32 v19, v20, v21
	v_cvt_pk_bf16_f32 v20, v22, v23
	v_cvt_pk_bf16_f32 v21, v24, v175
	ds_write_b128 v168, v[18:21] offset:34816
	ds_read_b128 v[18:21], v167
	ds_read_b128 v[22:25], v167 offset:16
	ds_read_b128 v[30:33], v167 offset:32
	ds_read_b128 v[42:45], v167 offset:48
	v_lshlrev_b32_e32 v46, 16, v38
	s_waitcnt lgkmcnt(3)
	v_sub_f32_e32 v18, v46, v18
	v_mul_f32_e32 v18, v19, v18
	v_and_b32_e32 v19, 0xffff0000, v38
	v_sub_f32_e32 v19, v19, v20
	v_mul_f32_e32 v19, v21, v19
	v_lshlrev_b32_e32 v20, 16, v39
	v_and_b32_e32 v21, 0xffff0000, v39
	s_waitcnt lgkmcnt(2)
	v_sub_f32_e32 v20, v20, v22
	v_sub_f32_e32 v21, v21, v24
	v_mul_f32_e32 v20, v23, v20
	v_mul_f32_e32 v21, v25, v21
	v_lshlrev_b32_e32 v22, 16, v40
	v_and_b32_e32 v23, 0xffff0000, v40
	v_lshlrev_b32_e32 v24, 16, v41
	v_and_b32_e32 v25, 0xffff0000, v41
	s_waitcnt lgkmcnt(1)
	v_sub_f32_e32 v22, v22, v30
	v_sub_f32_e32 v23, v23, v32
	s_waitcnt lgkmcnt(0)
	v_sub_f32_e32 v24, v24, v42
	v_sub_f32_e32 v25, v25, v44
	v_fma_f32 v18, v174, v18, v173
	v_fma_f32 v19, v174, v19, v173
	v_fma_f32 v20, v174, v20, v173
	v_fma_f32 v21, v174, v21, v173
	v_mul_f32_e32 v22, v31, v22
	v_mul_f32_e32 v23, v33, v23
	v_mul_f32_e32 v24, v43, v24
	v_mul_f32_e32 v25, v45, v25
	v_fma_f32 v22, v174, v22, v173
	v_fma_f32 v23, v174, v23, v173
	v_fma_f32 v24, v174, v24, v173
	v_fmac_f32_e32 v173, v174, v25
	v_cvt_pk_bf16_f32 v18, v18, v19
	v_cvt_pk_bf16_f32 v19, v20, v21
	v_cvt_pk_bf16_f32 v20, v22, v23
	v_cvt_pk_bf16_f32 v21, v24, v173
	ds_write_b128 v168, v[18:21] offset:43520
	ds_read_b128 v[18:21], v167
	ds_read_b128 v[22:25], v167 offset:16
	ds_read_b128 v[30:33], v167 offset:32
	ds_read_b128 v[38:41], v167 offset:48
	v_lshlrev_b32_e32 v42, 16, v34
	s_waitcnt lgkmcnt(3)
	v_sub_f32_e32 v18, v42, v18
	v_mul_f32_e32 v18, v19, v18
	v_and_b32_e32 v19, 0xffff0000, v34
	v_sub_f32_e32 v19, v19, v20
	v_mul_f32_e32 v19, v21, v19
	v_lshlrev_b32_e32 v20, 16, v35
	v_and_b32_e32 v21, 0xffff0000, v35
	s_waitcnt lgkmcnt(2)
	v_sub_f32_e32 v20, v20, v22
	v_sub_f32_e32 v21, v21, v24
	v_mul_f32_e32 v20, v23, v20
	v_mul_f32_e32 v21, v25, v21
	v_lshlrev_b32_e32 v22, 16, v36
	v_and_b32_e32 v23, 0xffff0000, v36
	v_lshlrev_b32_e32 v24, 16, v37
	v_and_b32_e32 v25, 0xffff0000, v37
	s_waitcnt lgkmcnt(1)
	v_sub_f32_e32 v22, v22, v30
	v_sub_f32_e32 v23, v23, v32
	s_waitcnt lgkmcnt(0)
	v_sub_f32_e32 v24, v24, v38
	v_sub_f32_e32 v25, v25, v40
	v_fma_f32 v18, v172, v18, v171
	v_fma_f32 v19, v172, v19, v171
	v_fma_f32 v20, v172, v20, v171
	v_fma_f32 v21, v172, v21, v171
	v_mul_f32_e32 v22, v31, v22
	v_mul_f32_e32 v23, v33, v23
	v_mul_f32_e32 v24, v39, v24
	v_mul_f32_e32 v25, v41, v25
	v_fma_f32 v22, v172, v22, v171
	v_fma_f32 v23, v172, v23, v171
	v_fma_f32 v24, v172, v24, v171
	v_fmac_f32_e32 v171, v172, v25
	v_cvt_pk_bf16_f32 v18, v18, v19
	v_cvt_pk_bf16_f32 v19, v20, v21
	v_cvt_pk_bf16_f32 v20, v22, v23
	v_cvt_pk_bf16_f32 v21, v24, v171
	ds_write_b128 v168, v[18:21] offset:52224
	ds_read_b128 v[18:21], v167
	ds_read_b128 v[22:25], v167 offset:16
	ds_read_b128 v[30:33], v167 offset:32
	ds_read_b128 v[34:37], v167 offset:48
	v_lshlrev_b32_e32 v38, 16, v26
	s_waitcnt lgkmcnt(3)
	v_sub_f32_e32 v18, v38, v18
	v_mul_f32_e32 v18, v19, v18
	v_and_b32_e32 v19, 0xffff0000, v26
	v_sub_f32_e32 v19, v19, v20
	v_mul_f32_e32 v19, v21, v19
	v_lshlrev_b32_e32 v20, 16, v27
	v_and_b32_e32 v21, 0xffff0000, v27
	s_waitcnt lgkmcnt(2)
	v_sub_f32_e32 v20, v20, v22
	v_sub_f32_e32 v21, v21, v24
	v_mul_f32_e32 v20, v23, v20
	v_mul_f32_e32 v21, v25, v21
	v_lshlrev_b32_e32 v22, 16, v28
	v_and_b32_e32 v23, 0xffff0000, v28
	v_lshlrev_b32_e32 v24, 16, v29
	v_and_b32_e32 v25, 0xffff0000, v29
	v_fma_f32 v18, v170, v18, v169
	s_waitcnt lgkmcnt(1)
	v_sub_f32_e32 v22, v22, v30
	v_sub_f32_e32 v23, v23, v32
	s_waitcnt lgkmcnt(0)
	v_sub_f32_e32 v24, v24, v34
	v_sub_f32_e32 v25, v25, v36
	v_fma_f32 v19, v170, v19, v169
	v_fma_f32 v20, v170, v20, v169
	v_fma_f32 v21, v170, v21, v169
	v_mul_f32_e32 v22, v31, v22
	v_mul_f32_e32 v23, v33, v23
	v_mul_f32_e32 v24, v35, v24
	v_mul_f32_e32 v25, v37, v25
	v_cvt_pk_bf16_f32 v18, v18, v19
	v_fma_f32 v22, v170, v22, v169
	v_fma_f32 v23, v170, v23, v169
	v_fma_f32 v24, v170, v24, v169
	v_fmac_f32_e32 v169, v170, v25
	v_cvt_pk_bf16_f32 v19, v20, v21
	v_cvt_pk_bf16_f32 v20, v22, v23
	v_cvt_pk_bf16_f32 v21, v24, v169
	ds_write_b128 v168, v[18:21] offset:60928
	v_add_co_u32_e32 v18, vcc, s15, v140
	s_mov_b32 s15, 0xa00000
	s_nop 0
	v_addc_co_u32_e32 v19, vcc, 0, v141, vcc
	s_waitcnt lgkmcnt(0)
	s_barrier
	global_load_dwordx4 v[46:49], v[18:19], off nt
	global_load_dword v96, v[142:143], off offset:1024
	global_load_dword v97, v[144:145], off offset:1024
	v_add_co_u32_e32 v18, vcc, s15, v140
	s_mov_b32 s15, 0xc00000
	s_nop 0
	v_addc_co_u32_e32 v19, vcc, 0, v141, vcc
	global_load_dwordx4 v[38:41], v[18:19], off nt
	global_load_dword v94, v[142:143], off offset:1152
	global_load_dword v95, v[144:145], off offset:1152
	v_add_co_u32_e32 v18, vcc, s15, v140
	s_mov_b32 s15, 0xe00000
	s_nop 0
	v_addc_co_u32_e32 v19, vcc, 0, v141, vcc
	global_load_dwordx4 v[34:37], v[18:19], off nt
	global_load_dword v92, v[142:143], off offset:1280
	global_load_dword v93, v[144:145], off offset:1280
	v_add_co_u32_e32 v18, vcc, s15, v140
	s_nop 1
	v_addc_co_u32_e32 v19, vcc, 0, v141, vcc
	global_load_dwordx4 v[26:29], v[18:19], off nt
	global_load_dword v90, v[142:143], off offset:1408
	global_load_dword v91, v[144:145], off offset:1408
	global_load_dwordx4 v[78:81], v[146:147], off offset:512 nt
	global_load_dwordx4 v[74:77], v[148:149], off offset:512 nt
	global_load_dwordx4 v[70:73], v[150:151], off offset:512 nt
	global_load_dwordx4 v[66:69], v[152:153], off offset:512 nt
	ds_read_b128 v[18:21], v160 offset:34816
	ds_read_b128 v[22:25], v165
	ds_read_b128 v[30:33], v165 offset:4352
	ds_read_b128 v[42:45], v165 offset:8704
	ds_read_b128 v[140:143], v165 offset:13056
	ds_read_b128 v[144:147], v165 offset:17408
	ds_read_b128 v[148:151], v165 offset:21760
	ds_read_b128 v[152:155], v165 offset:26112
	ds_read_b128 v[170:173], v165 offset:30464
	s_waitcnt lgkmcnt(7)
	v_mfma_f32_16x16x32_bf16 v[22:25], v[18:21], v[22:25], 0
	s_and_b64 vcc, exec, s[12:13]
	s_waitcnt lgkmcnt(6)
	v_mfma_f32_16x16x32_bf16 v[30:33], v[18:21], v[30:33], 0
	s_waitcnt lgkmcnt(5)
	v_mfma_f32_16x16x32_bf16 v[42:45], v[18:21], v[42:45], 0
	s_waitcnt lgkmcnt(4)
	v_mfma_f32_16x16x32_bf16 v[140:143], v[18:21], v[140:143], 0
	s_waitcnt lgkmcnt(3)
	v_mfma_f32_16x16x32_bf16 v[144:147], v[18:21], v[144:147], 0
	s_waitcnt lgkmcnt(2)
	v_mfma_f32_16x16x32_bf16 v[148:151], v[18:21], v[148:151], 0
	s_waitcnt lgkmcnt(1)
	v_mfma_f32_16x16x32_bf16 v[152:155], v[18:21], v[152:155], 0
	s_waitcnt lgkmcnt(0)
	v_mfma_f32_16x16x32_bf16 v[18:21], v[18:21], v[170:173], 0
	ds_read_b128 v[170:173], v160 offset:34880
	ds_read_b128 v[174:177], v165 offset:64
	s_waitcnt lgkmcnt(0)
	v_mfma_f32_16x16x32_bf16 v[22:25], v[170:173], v[174:177], v[22:25]
	ds_read_b128 v[174:177], v165 offset:4416
	s_waitcnt lgkmcnt(0)
	v_mfma_f32_16x16x32_bf16 v[30:33], v[170:173], v[174:177], v[30:33]
	ds_read_b128 v[174:177], v165 offset:8768
	s_waitcnt lgkmcnt(0)
	v_mfma_f32_16x16x32_bf16 v[42:45], v[170:173], v[174:177], v[42:45]
	ds_read_b128 v[174:177], v165 offset:13120
	s_waitcnt lgkmcnt(0)
	v_mfma_f32_16x16x32_bf16 v[140:143], v[170:173], v[174:177], v[140:143]
	ds_read_b128 v[174:177], v165 offset:17472
	s_waitcnt lgkmcnt(0)
	v_mfma_f32_16x16x32_bf16 v[144:147], v[170:173], v[174:177], v[144:147]
	ds_read_b128 v[174:177], v165 offset:21824
	s_waitcnt lgkmcnt(0)
	v_mfma_f32_16x16x32_bf16 v[148:151], v[170:173], v[174:177], v[148:151]
	ds_read_b128 v[174:177], v165 offset:26176
	s_waitcnt lgkmcnt(0)
	v_mfma_f32_16x16x32_bf16 v[152:155], v[170:173], v[174:177], v[152:155]
	ds_read_b128 v[174:177], v165 offset:30528
	s_waitcnt lgkmcnt(0)
	v_mfma_f32_16x16x32_bf16 v[18:21], v[170:173], v[174:177], v[18:21]
	ds_read_b128 v[170:173], v160 offset:34944
	ds_read_b128 v[174:177], v165 offset:128
	s_waitcnt lgkmcnt(0)
	v_mfma_f32_16x16x32_bf16 v[174:177], v[170:173], v[174:177], v[22:25]
	s_nop 2
	ds_read_b128 v[22:25], v165 offset:4480
	s_waitcnt lgkmcnt(0)
	v_mfma_f32_16x16x32_bf16 v[30:33], v[170:173], v[22:25], v[30:33]
	ds_read_b128 v[22:25], v165 offset:8832
	s_waitcnt lgkmcnt(0)
	v_mfma_f32_16x16x32_bf16 v[42:45], v[170:173], v[22:25], v[42:45]
	ds_read_b128 v[22:25], v165 offset:13184
	s_waitcnt lgkmcnt(0)
	v_mfma_f32_16x16x32_bf16 v[140:143], v[170:173], v[22:25], v[140:143]
	ds_read_b128 v[22:25], v165 offset:17536
	s_waitcnt lgkmcnt(0)
	v_mfma_f32_16x16x32_bf16 v[144:147], v[170:173], v[22:25], v[144:147]
	ds_read_b128 v[22:25], v165 offset:21888
	s_waitcnt lgkmcnt(0)
	v_mfma_f32_16x16x32_bf16 v[148:151], v[170:173], v[22:25], v[148:151]
	ds_read_b128 v[22:25], v165 offset:26240
	s_waitcnt lgkmcnt(0)
	v_mfma_f32_16x16x32_bf16 v[152:155], v[170:173], v[22:25], v[152:155]
	ds_read_b128 v[22:25], v165 offset:30592
	s_waitcnt lgkmcnt(0)
	v_mfma_f32_16x16x32_bf16 v[22:25], v[170:173], v[22:25], v[18:21]
	ds_read_b128 v[170:173], v160 offset:35008
	s_nop 1
	ds_read_b128 v[18:21], v165 offset:192
	s_waitcnt lgkmcnt(0)
	v_mfma_f32_16x16x32_bf16 v[174:177], v[170:173], v[18:21], v[174:177]
	ds_read_b128 v[18:21], v165 offset:4544
	s_waitcnt lgkmcnt(0)
	v_mfma_f32_16x16x32_bf16 v[178:181], v[170:173], v[18:21], v[30:33]
	ds_read_b128 v[18:21], v165 offset:8896
	s_waitcnt lgkmcnt(0)
	v_mfma_f32_16x16x32_bf16 v[188:191], v[170:173], v[18:21], v[42:45]
	ds_read_b128 v[18:21], v165 offset:13248
	s_waitcnt lgkmcnt(0)
	v_mfma_f32_16x16x32_bf16 v[140:143], v[170:173], v[18:21], v[140:143]
	ds_read_b128 v[18:21], v165 offset:17600
	s_waitcnt lgkmcnt(0)
	v_mfma_f32_16x16x32_bf16 v[30:33], v[170:173], v[18:21], v[144:147]
	ds_read_b128 v[18:21], v165 offset:21952
	s_nop 1
	ds_read_b128 v[144:147], v165 offset:30656
	s_waitcnt lgkmcnt(0)
	v_mfma_f32_16x16x32_bf16 v[22:25], v[170:173], v[144:147], v[22:25]
	ds_read2_b32 v[144:145], v161 offset1:16
	v_lshlrev_b32_e32 v147, 16, v62
	v_and_b32_e32 v62, 0xffff0000, v62
	v_mfma_f32_16x16x32_bf16 v[42:45], v[170:173], v[18:21], v[148:151]
	ds_read_b128 v[18:21], v165 offset:26304
	s_waitcnt lgkmcnt(1)
	v_add_f32_e32 v146, v174, v144
	v_mul_f32_e32 v146, v146, v147
	v_add_f32_e32 v147, v175, v144
	v_mul_f32_e32 v62, v147, v62
	v_cvt_pk_bf16_f32 v62, v146, v62
	v_add_f32_e32 v146, v176, v144
	v_lshlrev_b32_e32 v147, 16, v63
	v_add_f32_e32 v144, v177, v144
	v_and_b32_e32 v63, 0xffff0000, v63
	v_mul_f32_e32 v146, v146, v147
	v_mul_f32_e32 v63, v144, v63
	v_cvt_pk_bf16_f32 v63, v146, v63
	v_add_f32_e32 v144, v178, v145
	v_lshlrev_b32_e32 v146, 16, v64
	v_mul_f32_e32 v144, v144, v146
	v_add_f32_e32 v146, v179, v145
	v_and_b32_e32 v64, 0xffff0000, v64
	v_mul_f32_e32 v64, v146, v64
	v_cvt_pk_bf16_f32 v64, v144, v64
	v_add_f32_e32 v144, v180, v145
	v_lshlrev_b32_e32 v146, 16, v65
	v_add_f32_e32 v145, v181, v145
	v_and_b32_e32 v65, 0xffff0000, v65
	v_mul_f32_e32 v65, v145, v65
	v_mul_f32_e32 v144, v144, v146
	v_cvt_pk_bf16_f32 v65, v144, v65
	v_permlane16_swap_b32_e32 v62, v64
	v_permlane16_swap_b32_e32 v63, v65
	global_store_dwordx4 v[88:89], v[62:65], off offset:256
	ds_read2_b32 v[62:63], v161 offset0:32 offset1:48
	s_waitcnt lgkmcnt(1)
	v_mfma_f32_16x16x32_bf16 v[18:21], v[170:173], v[18:21], v[152:155]
	v_lshlrev_b32_e32 v65, 16, v58
	v_and_b32_e32 v58, 0xffff0000, v58
	s_waitcnt lgkmcnt(0)
	v_add_f32_e32 v64, v188, v62
	v_mul_f32_e32 v64, v64, v65
	v_add_f32_e32 v65, v189, v62
	v_mul_f32_e32 v58, v65, v58
	v_cvt_pk_bf16_f32 v58, v64, v58
	v_add_f32_e32 v64, v190, v62
	v_lshlrev_b32_e32 v65, 16, v59
	v_add_f32_e32 v62, v191, v62
	v_and_b32_e32 v59, 0xffff0000, v59
	v_mul_f32_e32 v64, v64, v65
	v_mul_f32_e32 v59, v62, v59
	v_cvt_pk_bf16_f32 v59, v64, v59
	v_add_f32_e32 v62, v140, v63
	v_lshlrev_b32_e32 v64, 16, v60
	v_mul_f32_e32 v62, v62, v64
	v_add_f32_e32 v64, v141, v63
	v_and_b32_e32 v60, 0xffff0000, v60
	v_mul_f32_e32 v60, v64, v60
	v_cvt_pk_bf16_f32 v60, v62, v60
	v_add_f32_e32 v62, v142, v63
	v_lshlrev_b32_e32 v64, 16, v61
	v_add_f32_e32 v63, v143, v63
	v_and_b32_e32 v61, 0xffff0000, v61
	v_mul_f32_e32 v61, v63, v61
	v_mul_f32_e32 v62, v62, v64
	v_cvt_pk_bf16_f32 v61, v62, v61
	v_permlane16_swap_b32_e32 v58, v60
	v_permlane16_swap_b32_e32 v59, v61
	global_store_dwordx4 v[86:87], v[58:61], off offset:256
	ds_read2_b32 v[58:59], v161 offset0:64 offset1:80
	s_waitcnt lgkmcnt(0)
	v_add_f32_e32 v30, v30, v58
	v_lshlrev_b32_e32 v60, 16, v54
	v_add_f32_e32 v31, v31, v58
	v_and_b32_e32 v54, 0xffff0000, v54
	v_mul_f32_e32 v30, v30, v60
	v_mul_f32_e32 v31, v31, v54
	v_cvt_pk_bf16_f32 v30, v30, v31
	v_add_f32_e32 v31, v32, v58
	v_lshlrev_b32_e32 v32, 16, v55
	v_mul_f32_e32 v31, v31, v32
	v_add_f32_e32 v32, v33, v58
	v_and_b32_e32 v33, 0xffff0000, v55
	v_mul_f32_e32 v32, v32, v33
	v_cvt_pk_bf16_f32 v31, v31, v32
	v_add_f32_e32 v32, v42, v59
	v_lshlrev_b32_e32 v33, 16, v56
	v_mul_f32_e32 v32, v32, v33
	v_add_f32_e32 v33, v43, v59
	v_and_b32_e32 v42, 0xffff0000, v56
	v_mul_f32_e32 v33, v33, v42
	v_cvt_pk_bf16_f32 v32, v32, v33
	v_add_f32_e32 v33, v44, v59
	v_lshlrev_b32_e32 v42, 16, v57
	v_mul_f32_e32 v33, v33, v42
	v_add_f32_e32 v42, v45, v59
	v_and_b32_e32 v43, 0xffff0000, v57
	v_mul_f32_e32 v42, v42, v43
	v_cvt_pk_bf16_f32 v33, v33, v42
	v_permlane16_swap_b32_e32 v30, v32
	v_permlane16_swap_b32_e32 v31, v33
	global_store_dwordx4 v[82:83], v[30:33], off offset:256
	ds_read2_b32 v[30:31], v161 offset0:96 offset1:112
	s_waitcnt lgkmcnt(0)
	v_add_f32_e32 v18, v18, v30
	s_waitcnt vmcnt(23)
	v_mov_b32_e32 v32, v52
	s_nop 1
	v_permlane16_swap_b32_e32 v50, v32
	v_lshlrev_b32_e32 v42, 16, v50
	v_mov_b32_e32 v33, v53
	v_mul_f32_e32 v18, v18, v42
	v_add_f32_e32 v19, v19, v30
	v_and_b32_e32 v42, 0xffff0000, v50
	v_permlane16_swap_b32_e32 v51, v33
	v_mul_f32_e32 v19, v19, v42
	v_cvt_pk_bf16_f32 v18, v18, v19
	v_add_f32_e32 v19, v20, v30
	v_lshlrev_b32_e32 v20, 16, v51
	v_mul_f32_e32 v19, v19, v20
	v_add_f32_e32 v20, v21, v30
	v_and_b32_e32 v21, 0xffff0000, v51
	v_mul_f32_e32 v20, v20, v21
	v_cvt_pk_bf16_f32 v19, v19, v20
	v_add_f32_e32 v20, v22, v31
	v_lshlrev_b32_e32 v21, 16, v32
	v_mul_f32_e32 v20, v20, v21
	v_add_f32_e32 v21, v23, v31
	v_and_b32_e32 v22, 0xffff0000, v32
	v_mul_f32_e32 v21, v21, v22
	v_cvt_pk_bf16_f32 v20, v20, v21
	v_add_f32_e32 v21, v24, v31
	v_lshlrev_b32_e32 v22, 16, v33
	v_mul_f32_e32 v21, v21, v22
	v_add_f32_e32 v22, v25, v31
	v_and_b32_e32 v23, 0xffff0000, v33
	v_mul_f32_e32 v22, v22, v23
	v_cvt_pk_bf16_f32 v21, v21, v22
	v_permlane16_swap_b32_e32 v18, v20
	v_permlane16_swap_b32_e32 v19, v21
	global_store_dwordx4 v[84:85], v[18:21], off offset:256
	ds_read_b128 v[18:21], v167
	ds_read_b128 v[22:25], v167 offset:16
	ds_read_b128 v[30:33], v167 offset:32
	ds_read_b128 v[42:45], v167 offset:48
	s_waitcnt vmcnt(19)
	v_lshlrev_b32_e32 v50, 16, v46
	s_waitcnt lgkmcnt(3)
	v_sub_f32_e32 v18, v50, v18
	v_mul_f32_e32 v18, v19, v18
	v_and_b32_e32 v19, 0xffff0000, v46
	v_sub_f32_e32 v19, v19, v20
	v_mul_f32_e32 v19, v21, v19
	v_lshlrev_b32_e32 v20, 16, v47
	v_and_b32_e32 v21, 0xffff0000, v47
	s_waitcnt lgkmcnt(2)
	v_sub_f32_e32 v20, v20, v22
	v_sub_f32_e32 v21, v21, v24
	v_mul_f32_e32 v20, v23, v20
	v_mul_f32_e32 v21, v25, v21
	v_lshlrev_b32_e32 v22, 16, v48
	v_and_b32_e32 v23, 0xffff0000, v48
	v_lshlrev_b32_e32 v24, 16, v49
	v_and_b32_e32 v25, 0xffff0000, v49
	s_waitcnt lgkmcnt(1)
	v_sub_f32_e32 v22, v22, v30
	v_sub_f32_e32 v23, v23, v32
	s_waitcnt lgkmcnt(0)
	v_sub_f32_e32 v24, v24, v42
	v_sub_f32_e32 v25, v25, v44
	s_waitcnt vmcnt(17)
	v_fma_f32 v18, v96, v18, v97
	v_fma_f32 v19, v96, v19, v97
	v_fma_f32 v20, v96, v20, v97
	v_fma_f32 v21, v96, v21, v97
	v_mul_f32_e32 v22, v31, v22
	v_mul_f32_e32 v23, v33, v23
	v_mul_f32_e32 v24, v43, v24
	v_mul_f32_e32 v25, v45, v25
	v_fma_f32 v22, v96, v22, v97
	v_fma_f32 v23, v96, v23, v97
	v_fma_f32 v24, v96, v24, v97
	v_fma_f32 v25, v96, v25, v97
	v_cvt_pk_bf16_f32 v18, v18, v19
	v_cvt_pk_bf16_f32 v19, v20, v21
	v_cvt_pk_bf16_f32 v20, v22, v23
	v_cvt_pk_bf16_f32 v21, v24, v25
	ds_write_b128 v168, v[18:21]
	ds_read_b128 v[18:21], v167
	ds_read_b128 v[22:25], v167 offset:16
	ds_read_b128 v[30:33], v167 offset:32
	ds_read_b128 v[42:45], v167 offset:48
	s_waitcnt vmcnt(16)
	v_lshlrev_b32_e32 v50, 16, v38
	s_waitcnt lgkmcnt(3)
	v_sub_f32_e32 v18, v50, v18
	v_mul_f32_e32 v18, v19, v18
	v_and_b32_e32 v19, 0xffff0000, v38
	v_sub_f32_e32 v19, v19, v20
	v_mul_f32_e32 v19, v21, v19
	v_lshlrev_b32_e32 v20, 16, v39
	v_and_b32_e32 v21, 0xffff0000, v39
	s_waitcnt lgkmcnt(2)
	v_sub_f32_e32 v20, v20, v22
	v_sub_f32_e32 v21, v21, v24
	v_mul_f32_e32 v20, v23, v20
	v_mul_f32_e32 v21, v25, v21
	v_lshlrev_b32_e32 v22, 16, v40
	v_and_b32_e32 v23, 0xffff0000, v40
	v_lshlrev_b32_e32 v24, 16, v41
	v_and_b32_e32 v25, 0xffff0000, v41
	s_waitcnt lgkmcnt(1)
	v_sub_f32_e32 v22, v22, v30
	v_sub_f32_e32 v23, v23, v32
	s_waitcnt lgkmcnt(0)
	v_sub_f32_e32 v24, v24, v42
	v_sub_f32_e32 v25, v25, v44
	s_waitcnt vmcnt(14)
	v_fma_f32 v18, v94, v18, v95
	v_fma_f32 v19, v94, v19, v95
	v_fma_f32 v20, v94, v20, v95
	v_fma_f32 v21, v94, v21, v95
	v_mul_f32_e32 v22, v31, v22
	v_mul_f32_e32 v23, v33, v23
	v_mul_f32_e32 v24, v43, v24
	v_mul_f32_e32 v25, v45, v25
	v_fma_f32 v22, v94, v22, v95
	v_fma_f32 v23, v94, v23, v95
	v_fma_f32 v24, v94, v24, v95
	v_fma_f32 v25, v94, v25, v95
	v_cvt_pk_bf16_f32 v18, v18, v19
	v_cvt_pk_bf16_f32 v19, v20, v21
	v_cvt_pk_bf16_f32 v20, v22, v23
	v_cvt_pk_bf16_f32 v21, v24, v25
	ds_write_b128 v168, v[18:21] offset:8704
	ds_read_b128 v[18:21], v167
	ds_read_b128 v[22:25], v167 offset:16
	ds_read_b128 v[30:33], v167 offset:32
	ds_read_b128 v[42:45], v167 offset:48
	s_waitcnt vmcnt(13)
	v_lshlrev_b32_e32 v50, 16, v34
	s_waitcnt lgkmcnt(3)
	v_sub_f32_e32 v18, v50, v18
	v_mul_f32_e32 v18, v19, v18
	v_and_b32_e32 v19, 0xffff0000, v34
	v_sub_f32_e32 v19, v19, v20
	v_mul_f32_e32 v19, v21, v19
	v_lshlrev_b32_e32 v20, 16, v35
	v_and_b32_e32 v21, 0xffff0000, v35
	s_waitcnt lgkmcnt(2)
	v_sub_f32_e32 v20, v20, v22
	v_sub_f32_e32 v21, v21, v24
	v_mul_f32_e32 v20, v23, v20
	v_mul_f32_e32 v21, v25, v21
	v_lshlrev_b32_e32 v22, 16, v36
	v_and_b32_e32 v23, 0xffff0000, v36
	v_lshlrev_b32_e32 v24, 16, v37
	v_and_b32_e32 v25, 0xffff0000, v37
	s_waitcnt lgkmcnt(1)
	v_sub_f32_e32 v22, v22, v30
	v_sub_f32_e32 v23, v23, v32
	s_waitcnt lgkmcnt(0)
	v_sub_f32_e32 v24, v24, v42
	v_sub_f32_e32 v25, v25, v44
	s_waitcnt vmcnt(11)
	v_fma_f32 v18, v92, v18, v93
	v_fma_f32 v19, v92, v19, v93
	v_fma_f32 v20, v92, v20, v93
	v_fma_f32 v21, v92, v21, v93
	v_mul_f32_e32 v22, v31, v22
	v_mul_f32_e32 v23, v33, v23
	v_mul_f32_e32 v24, v43, v24
	v_mul_f32_e32 v25, v45, v25
	v_fma_f32 v22, v92, v22, v93
	v_fma_f32 v23, v92, v23, v93
	v_fma_f32 v24, v92, v24, v93
	v_fma_f32 v25, v92, v25, v93
	v_cvt_pk_bf16_f32 v18, v18, v19
	v_cvt_pk_bf16_f32 v19, v20, v21
	v_cvt_pk_bf16_f32 v20, v22, v23
	v_cvt_pk_bf16_f32 v21, v24, v25
	ds_write_b128 v168, v[18:21] offset:17408
	ds_read_b128 v[18:21], v167
	ds_read_b128 v[22:25], v167 offset:16
	ds_read_b128 v[30:33], v167 offset:32
	ds_read_b128 v[42:45], v167 offset:48
	s_waitcnt vmcnt(10)
	v_lshlrev_b32_e32 v50, 16, v26
	s_waitcnt lgkmcnt(3)
	v_sub_f32_e32 v18, v50, v18
	v_mul_f32_e32 v18, v19, v18
	v_and_b32_e32 v19, 0xffff0000, v26
	v_sub_f32_e32 v19, v19, v20
	v_mul_f32_e32 v19, v21, v19
	v_lshlrev_b32_e32 v20, 16, v27
	v_and_b32_e32 v21, 0xffff0000, v27
	s_waitcnt lgkmcnt(2)
	v_sub_f32_e32 v20, v20, v22
	v_sub_f32_e32 v21, v21, v24
	v_mul_f32_e32 v20, v23, v20
	v_mul_f32_e32 v21, v25, v21
	v_lshlrev_b32_e32 v22, 16, v28
	v_and_b32_e32 v23, 0xffff0000, v28
	v_lshlrev_b32_e32 v24, 16, v29
	v_and_b32_e32 v25, 0xffff0000, v29
	s_waitcnt lgkmcnt(1)
	v_sub_f32_e32 v22, v22, v30
	v_sub_f32_e32 v23, v23, v32
	s_waitcnt lgkmcnt(0)
	v_sub_f32_e32 v24, v24, v42
	v_sub_f32_e32 v25, v25, v44
	s_waitcnt vmcnt(8)
	v_fma_f32 v18, v90, v18, v91
	v_fma_f32 v19, v90, v19, v91
	v_fma_f32 v20, v90, v20, v91
	v_fma_f32 v21, v90, v21, v91
	v_mul_f32_e32 v22, v31, v22
	v_mul_f32_e32 v23, v33, v23
	v_mul_f32_e32 v24, v43, v24
	v_mul_f32_e32 v25, v45, v25
	v_fma_f32 v22, v90, v22, v91
	v_fma_f32 v23, v90, v23, v91
	v_fma_f32 v24, v90, v24, v91
	v_fma_f32 v25, v90, v25, v91
	v_cvt_pk_bf16_f32 v18, v18, v19
	v_cvt_pk_bf16_f32 v19, v20, v21
	v_cvt_pk_bf16_f32 v20, v22, v23
	v_cvt_pk_bf16_f32 v21, v24, v25
	ds_write_b128 v168, v[18:21] offset:26112
	s_waitcnt lgkmcnt(0)
	s_barrier
	s_cbranch_vccnz .LBB0_922
	s_lshl_b32 s16, s14, 4
	s_and_b32 s15, s14, 7
	s_cmp_lg_u32 s15, 0
	s_cbranch_scc0 .LBB0_923
	s_lshl_b32 s17, s15, 7
	s_and_saveexec_b64 s[18:19], s[4:5]
	s_cbranch_execz .LBB0_911
	s_branch .LBB0_924

.LBB0_926:
	s_andn2_b64 vcc, exec, s[4:5]
	s_cbranch_vccnz .LBB0_974
	s_load_dwordx2 s[8:9], s[0:1], 0x18
	v_readlane_b32 s6, v254, 33
	s_waitcnt vmcnt(18)
	v_mov_b32_e32 v40, v237
	v_readlane_b32 s7, v254, 34
	v_mov_b32_e32 v2, v1
	v_lshlrev_b32_e32 v41, 3, v40
	v_cndmask_b32_e64 v0, 0, 1, s[6:7]
	v_cmp_ne_u32_e64 s[4:5], 1, v0
	s_andn2_b64 vcc, exec, s[6:7]
	v_ashrrev_i32_e32 v75, 3, v40
	v_and_b32_e32 v74, 56, v41
	s_cbranch_vccnz .LBB0_945
	v_readlane_b32 s6, v254, 39
	s_waitcnt vmcnt(4)
	v_mov_b32_e32 v18, v2
	v_mov_b32_e32 v19, v2
	v_add_u32_e32 v3, s6, v75
	v_mov_b32_e32 v20, v2
	v_mov_b32_e32 v21, v2
	v_mov_b64_e32 v[6:7], v[18:19]
	v_cmp_lt_i32_e32 vcc, -1, v3
	v_lshlrev_b32_e32 v0, 1, v74
	v_mov_b64_e32 v[8:9], v[20:21]
	s_and_saveexec_b64 s[6:7], vcc
	s_cbranch_execz .LBB0_930
	v_readlane_b32 s10, v254, 42
	v_readlane_b32 s11, v254, 43
	s_nop 0
	v_add_u32_e32 v6, s10, v3
	v_readlane_b32 s10, v254, 61
	v_readlane_b32 s11, v254, 62
	s_nop 1
	v_mov_b64_e32 v[4:5], s[10:11]
	s_movk_i32 s10, 0xa00
	v_mad_i64_i32 v[4:5], s[10:11], v6, s10, v[4:5]
	v_lshl_add_u64 v[4:5], v[4:5], 0, v[0:1]
	global_load_dwordx4 v[6:9], v[4:5], off offset:2048 nt
.LBB0_930:
	s_or_b64 exec, exec, s[6:7]
	s_movk_i32 s6, 0xffbf
	v_mov_b64_e32 v[10:11], v[18:19]
	v_cmp_lt_i32_e32 vcc, s6, v3
	v_mov_b64_e32 v[12:13], v[20:21]
	s_and_saveexec_b64 s[6:7], vcc
	s_cbranch_execz .LBB0_932
	v_readlane_b32 s10, v254, 40
	s_nop 1
	v_add_u32_e32 v10, s10, v3
	v_readlane_b32 s10, v254, 61
	v_readlane_b32 s11, v254, 62
	s_nop 1
	v_mov_b64_e32 v[4:5], s[10:11]
	s_movk_i32 s10, 0xa00
	v_mad_i64_i32 v[4:5], s[10:11], v10, s10, v[4:5]
	v_lshl_add_u64 v[4:5], v[4:5], 0, v[0:1]
	global_load_dwordx4 v[10:13], v[4:5], off offset:2048 nt
.LBB0_932:
	s_or_b64 exec, exec, s[6:7]
	v_readlane_b32 s6, v254, 38
	v_mov_b64_e32 v[14:15], v[18:19]
	v_mov_b64_e32 v[16:17], v[20:21]
	v_add_u32_e32 v4, s6, v75
	v_cmp_lt_i32_e32 vcc, -1, v4
	s_and_saveexec_b64 s[6:7], vcc
	s_cbranch_execz .LBB0_934
	v_readlane_b32 s10, v254, 42
	v_readlane_b32 s11, v254, 43
	s_nop 0
	v_add_u32_e32 v14, s10, v4
	v_readlane_b32 s10, v254, 61
	v_readlane_b32 s11, v254, 62
	s_nop 1
	v_mov_b64_e32 v[4:5], s[10:11]
	s_movk_i32 s10, 0xa00
	v_mad_i64_i32 v[4:5], s[10:11], v14, s10, v[4:5]
	v_lshl_add_u64 v[4:5], v[4:5], 0, v[0:1]
	global_load_dwordx4 v[14:17], v[4:5], off offset:2048 nt
.LBB0_934:
	s_or_b64 exec, exec, s[6:7]
	s_movk_i32 s6, 0xff3f
	v_mov_b64_e32 v[24:25], v[20:21]
	v_cmp_lt_i32_e32 vcc, s6, v3
	v_mov_b64_e32 v[22:23], v[18:19]
	s_and_saveexec_b64 s[6:7], vcc
	s_cbranch_execz .LBB0_936
	v_readlane_b32 s10, v254, 41
	s_nop 1
	v_add_u32_e32 v3, s10, v3
	v_readlane_b32 s10, v254, 61
	v_readlane_b32 s11, v254, 62
	s_nop 1
	v_mov_b64_e32 v[4:5], s[10:11]
	s_movk_i32 s10, 0xa00
	v_mad_i64_i32 v[4:5], s[10:11], v3, s10, v[4:5]
	v_lshl_add_u64 v[4:5], v[4:5], 0, v[0:1]
	global_load_dwordx4 v[22:25], v[4:5], off offset:2048 nt
.LBB0_936:
	s_or_b64 exec, exec, s[6:7]
	v_ashrrev_i32_e32 v3, 5, v40
	v_readlane_b32 s10, v254, 60
	v_and_b32_e32 v0, 0xf8, v41
	v_readlane_b32 s6, v254, 39
	v_add_u32_e32 v4, s10, v3
	v_readlane_b32 s10, v254, 44
	v_add_u32_e32 v0, s6, v0
	v_readlane_b32 s11, v254, 45
	v_mov_b64_e32 v[28:29], v[20:21]
	v_cmp_lt_i32_e64 s[6:7], -1, v0
	v_lshl_add_u64 v[38:39], v[0:1], 1, s[10:11]
	v_ashrrev_i32_e32 v5, 31, v4
	v_mov_b64_e32 v[26:27], v[18:19]
	s_and_saveexec_b64 s[10:11], s[6:7]
	s_cbranch_execz .LBB0_938
	v_lshlrev_b64 v[26:27], 16, v[4:5]
	v_lshl_add_u64 v[26:27], v[38:39], 0, v[26:27]
	global_load_dwordx4 v[26:29], v[26:27], off nt
.LBB0_938:
	s_or_b64 exec, exec, s[10:11]
	v_mov_b64_e32 v[32:33], v[20:21]
	v_mov_b64_e32 v[30:31], v[18:19]
	s_and_saveexec_b64 s[10:11], s[6:7]
	s_cbranch_execz .LBB0_940
	v_lshlrev_b64 v[30:31], 16, v[4:5]
	v_lshl_add_u64 v[30:31], v[38:39], 0, v[30:31]
	v_add_co_u32_e32 v30, vcc, 0x100000, v30
	s_nop 1
	v_addc_co_u32_e32 v31, vcc, 0, v31, vcc
	global_load_dwordx4 v[30:33], v[30:31], off nt
.LBB0_940:
	s_or_b64 exec, exec, s[10:11]
	s_and_saveexec_b64 s[10:11], s[6:7]
	s_cbranch_execz .LBB0_942
	v_lshlrev_b64 v[18:19], 16, v[4:5]
	v_lshl_add_u64 v[18:19], v[38:39], 0, v[18:19]
	v_add_co_u32_e32 v18, vcc, 0x200000, v18
	s_nop 1
	v_addc_co_u32_e32 v19, vcc, 0, v19, vcc
	global_load_dwordx4 v[18:21], v[18:19], off nt
.LBB0_942:
	s_or_b64 exec, exec, s[10:11]
	v_mov_b32_e32 v37, v2
	v_mov_b32_e32 v36, v2
	v_mov_b32_e32 v35, v2
	v_mov_b32_e32 v34, v2
	s_and_saveexec_b64 s[10:11], s[6:7]
	s_cbranch_execz .LBB0_944
	v_lshlrev_b64 v[4:5], 16, v[4:5]
	v_lshl_add_u64 v[4:5], v[38:39], 0, v[4:5]
	v_add_co_u32_e32 v4, vcc, 0x300000, v4
	s_nop 1
	v_addc_co_u32_e32 v5, vcc, 0, v5, vcc
	global_load_dwordx4 v[34:37], v[4:5], off nt
